# GEMM K-loops P1/P3/P4: LDS-DMA uses saddr+voffset addressing (16 VALU 64-bit adds per iteration removed)
# speedup vs baseline: 1.0050x; 1.0043x over previous
.LBB0_176:
	ds_read_b128 v[58:61], v219
	ds_read_b128 v[62:65], v219 offset:1024
	ds_read_b128 v[78:81], v219 offset:2048
	ds_read_b128 v[82:85], v219 offset:3072
	ds_read_b128 v[102:105], v220
	ds_read_b128 v[106:109], v220 offset:1024
	ds_read_b128 v[122:125], v220 offset:2048
	ds_read_b128 v[126:129], v220 offset:3072
	s_add_u32 s42, s40, 0xfff80080
	s_addc_u32 s43, s41, -1
	s_cmp_eq_u32 s52, 28
	s_cselect_b32 s45, s2, s43
	s_cselect_b32 s44, s29, s42
	s_cselect_b32 s43, s27, s47
	s_cselect_b32 s42, s39, s46
	s_add_i32 m0, s49, 0xc000
	ds_read_b128 v[146:149], v221
	ds_read_b128 v[150:153], v221 offset:1024
	ds_read_b128 v[170:173], v221 offset:2048
	ds_read_b128 v[174:177], v221 offset:3072
	ds_read_b128 v[178:181], v221 offset:4096
	ds_read_b128 v[182:185], v221 offset:5120
	ds_read_b128 v[186:189], v221 offset:6144
	ds_read_b128 v[190:193], v221 offset:7168
	global_load_lds_dwordx4 v206, s[40:41]
	s_add_i32 m0, s49, 0xe000
	s_nop 0
	global_load_lds_dwordx4 v208, s[40:41]
	s_waitcnt vmcnt(8)
	s_waitcnt lgkmcnt(0)
	s_barrier
	v_mfma_f32_16x16x32_bf16 v[166:169], v[58:61], v[146:149], v[166:169]
	v_mfma_f32_16x16x32_bf16 v[162:165], v[78:81], v[146:149], v[162:165]
	v_mfma_f32_16x16x32_bf16 v[142:145], v[58:61], v[170:173], v[142:145]
	v_mfma_f32_16x16x32_bf16 v[138:141], v[78:81], v[170:173], v[138:141]
	v_mfma_f32_16x16x32_bf16 v[118:121], v[58:61], v[178:181], v[118:121]
	v_mfma_f32_16x16x32_bf16 v[114:117], v[78:81], v[178:181], v[114:117]
	v_mfma_f32_16x16x32_bf16 v[94:97], v[58:61], v[186:189], v[94:97]
	v_mfma_f32_16x16x32_bf16 v[90:93], v[78:81], v[186:189], v[90:93]
	v_mfma_f32_16x16x32_bf16 v[166:169], v[62:65], v[150:153], v[166:169]
	v_mfma_f32_16x16x32_bf16 v[162:165], v[82:85], v[150:153], v[162:165]
	v_mfma_f32_16x16x32_bf16 v[142:145], v[62:65], v[174:177], v[142:145]
	v_mfma_f32_16x16x32_bf16 v[138:141], v[82:85], v[174:177], v[138:141]
	v_mfma_f32_16x16x32_bf16 v[118:121], v[62:65], v[182:185], v[118:121]
	v_mfma_f32_16x16x32_bf16 v[114:117], v[82:85], v[182:185], v[114:117]
	v_mfma_f32_16x16x32_bf16 v[94:97], v[62:65], v[190:193], v[94:97]
	v_mfma_f32_16x16x32_bf16 v[90:93], v[82:85], v[190:193], v[90:93]
	v_mfma_f32_16x16x32_bf16 v[158:161], v[102:105], v[146:149], v[158:161]
	v_mfma_f32_16x16x32_bf16 v[134:137], v[102:105], v[170:173], v[134:137]
	v_mfma_f32_16x16x32_bf16 v[130:133], v[122:125], v[170:173], v[130:133]
	v_mfma_f32_16x16x32_bf16 v[110:113], v[102:105], v[178:181], v[110:113]
	v_mfma_f32_16x16x32_bf16 v[98:101], v[122:125], v[178:181], v[98:101]
	v_mfma_f32_16x16x32_bf16 v[86:89], v[102:105], v[186:189], v[86:89]
	v_mfma_f32_16x16x32_bf16 v[74:77], v[122:125], v[186:189], v[74:77]
	v_mfma_f32_16x16x32_bf16 v[158:161], v[106:109], v[150:153], v[158:161]
	v_mfma_f32_16x16x32_bf16 v[146:149], v[122:125], v[146:149], v[154:157]
	v_mfma_f32_16x16x32_bf16 v[134:137], v[106:109], v[174:177], v[134:137]
	v_mfma_f32_16x16x32_bf16 v[130:133], v[126:129], v[174:177], v[130:133]
	v_mfma_f32_16x16x32_bf16 v[110:113], v[106:109], v[182:185], v[110:113]
	v_mfma_f32_16x16x32_bf16 v[98:101], v[126:129], v[182:185], v[98:101]
	v_mfma_f32_16x16x32_bf16 v[86:89], v[106:109], v[190:193], v[86:89]
	v_mfma_f32_16x16x32_bf16 v[74:77], v[126:129], v[190:193], v[74:77]
	v_mfma_f32_16x16x32_bf16 v[146:149], v[126:129], v[150:153], v[146:149]
	s_barrier
	s_add_i32 s53, s86, s48
	s_mov_b32 m0, s53
	ds_read_b128 v[150:153], v221 offset:16384
	ds_read_b128 v[154:157], v221 offset:17408
	ds_read_b128 v[170:173], v221 offset:18432
	ds_read_b128 v[174:177], v221 offset:19456
	ds_read_b128 v[178:181], v221 offset:20480
	ds_read_b128 v[182:185], v221 offset:21504
	ds_read_b128 v[186:189], v221 offset:22528
	ds_read_b128 v[190:193], v221 offset:23552
	global_load_lds_dwordx4 v198, s[42:43]
	s_add_i32 m0, s53, 0x2000
	s_add_u32 s54, s42, 0x80000
	s_addc_u32 s55, s43, 0
	s_add_i32 s53, s87, s48
	global_load_lds_dwordx4 v202, s[42:43]
	s_mov_b32 m0, s53
	s_nop 0
	global_load_lds_dwordx4 v198, s[54:55]
	s_add_i32 m0, s53, 0x2000
	s_nop 0
	global_load_lds_dwordx4 v202, s[54:55]
	s_mov_b32 m0, s49
	s_nop 0
	global_load_lds_dwordx4 v196, s[44:45]
	s_mov_b32 m0, s50
	s_nop 0
	global_load_lds_dwordx4 v200, s[44:45]
	s_waitcnt vmcnt(8)
	s_waitcnt lgkmcnt(0)
	s_barrier
	v_mfma_f32_16x16x32_bf16 v[70:73], v[58:61], v[150:153], v[70:73]
	v_mfma_f32_16x16x32_bf16 v[66:69], v[78:81], v[150:153], v[66:69]
	v_mfma_f32_16x16x32_bf16 v[46:49], v[58:61], v[170:173], v[46:49]
	v_mfma_f32_16x16x32_bf16 v[42:45], v[78:81], v[170:173], v[42:45]
	v_mfma_f32_16x16x32_bf16 v[30:33], v[58:61], v[178:181], v[30:33]
	v_mfma_f32_16x16x32_bf16 v[26:29], v[78:81], v[178:181], v[26:29]
	v_mfma_f32_16x16x32_bf16 v[14:17], v[58:61], v[186:189], v[14:17]
	v_mfma_f32_16x16x32_bf16 v[10:13], v[78:81], v[186:189], v[10:13]
	v_mfma_f32_16x16x32_bf16 v[70:73], v[62:65], v[154:157], v[70:73]
	v_mfma_f32_16x16x32_bf16 v[66:69], v[82:85], v[154:157], v[66:69]
	v_mfma_f32_16x16x32_bf16 v[46:49], v[62:65], v[174:177], v[46:49]
	v_mfma_f32_16x16x32_bf16 v[42:45], v[82:85], v[174:177], v[42:45]
	v_mfma_f32_16x16x32_bf16 v[30:33], v[62:65], v[182:185], v[30:33]
	v_mfma_f32_16x16x32_bf16 v[26:29], v[82:85], v[182:185], v[26:29]
	v_mfma_f32_16x16x32_bf16 v[14:17], v[62:65], v[190:193], v[14:17]
	v_mfma_f32_16x16x32_bf16 v[10:13], v[82:85], v[190:193], v[10:13]
	v_mfma_f32_16x16x32_bf16 v[54:57], v[102:105], v[150:153], v[54:57]
	v_mfma_f32_16x16x32_bf16 v[50:53], v[122:125], v[150:153], v[50:53]
	v_mfma_f32_16x16x32_bf16 v[38:41], v[102:105], v[170:173], v[38:41]
	v_mfma_f32_16x16x32_bf16 v[34:37], v[122:125], v[170:173], v[34:37]
	v_mfma_f32_16x16x32_bf16 v[22:25], v[102:105], v[178:181], v[22:25]
	v_mfma_f32_16x16x32_bf16 v[18:21], v[122:125], v[178:181], v[18:21]
	v_mfma_f32_16x16x32_bf16 v[6:9], v[102:105], v[186:189], v[6:9]
	v_mfma_f32_16x16x32_bf16 v[2:5], v[122:125], v[186:189], v[2:5]
	v_mfma_f32_16x16x32_bf16 v[54:57], v[106:109], v[154:157], v[54:57]
	v_mfma_f32_16x16x32_bf16 v[50:53], v[126:129], v[154:157], v[50:53]
	v_mfma_f32_16x16x32_bf16 v[38:41], v[106:109], v[174:177], v[38:41]
	v_mfma_f32_16x16x32_bf16 v[34:37], v[126:129], v[174:177], v[34:37]
	v_mfma_f32_16x16x32_bf16 v[22:25], v[106:109], v[182:185], v[22:25]
	v_mfma_f32_16x16x32_bf16 v[18:21], v[126:129], v[182:185], v[18:21]
	v_mfma_f32_16x16x32_bf16 v[6:9], v[106:109], v[190:193], v[6:9]
	v_mfma_f32_16x16x32_bf16 v[2:5], v[126:129], v[190:193], v[2:5]
	s_barrier
	s_add_i32 s53, 0, 0x18000
	s_add_i32 s54, 0, 0x1c000
	v_add_u32_e32 v82, s53, v218
	v_add_u32_e32 v126, s54, v218
	ds_read_b128 v[58:61], v82
	ds_read_b128 v[62:65], v82 offset:1024
	ds_read_b128 v[78:81], v82 offset:2048
	ds_read_b128 v[82:85], v82 offset:3072
	ds_read_b128 v[102:105], v126
	ds_read_b128 v[106:109], v126 offset:1024
	ds_read_b128 v[122:125], v126 offset:2048
	ds_read_b128 v[126:129], v126 offset:3072
	s_add_u32 s44, s44, 0x80000
	s_addc_u32 s45, s45, 0
	s_mov_b32 m0, s51
	ds_read_b128 v[150:153], v221 offset:32768
	ds_read_b128 v[154:157], v221 offset:33792
	ds_read_b128 v[170:173], v221 offset:34816
	ds_read_b128 v[174:177], v221 offset:35840
	ds_read_b128 v[178:181], v221 offset:36864
	ds_read_b128 v[182:185], v221 offset:37888
	ds_read_b128 v[186:189], v221 offset:38912
	ds_read_b128 v[190:193], v221 offset:39936
	global_load_lds_dwordx4 v196, s[44:45]
	s_mov_b32 m0, s72
	s_nop 0
	global_load_lds_dwordx4 v200, s[44:45]
	s_waitcnt vmcnt(8)
	s_waitcnt lgkmcnt(0)
	s_barrier
	v_mfma_f32_16x16x32_bf16 v[166:169], v[58:61], v[150:153], v[166:169]
	v_mfma_f32_16x16x32_bf16 v[162:165], v[78:81], v[150:153], v[162:165]
	v_mfma_f32_16x16x32_bf16 v[142:145], v[58:61], v[170:173], v[142:145]
	v_mfma_f32_16x16x32_bf16 v[138:141], v[78:81], v[170:173], v[138:141]
	v_mfma_f32_16x16x32_bf16 v[118:121], v[58:61], v[178:181], v[118:121]
	v_mfma_f32_16x16x32_bf16 v[114:117], v[78:81], v[178:181], v[114:117]
	v_mfma_f32_16x16x32_bf16 v[94:97], v[58:61], v[186:189], v[94:97]
	v_mfma_f32_16x16x32_bf16 v[90:93], v[78:81], v[186:189], v[90:93]
	v_mfma_f32_16x16x32_bf16 v[166:169], v[62:65], v[154:157], v[166:169]
	v_mfma_f32_16x16x32_bf16 v[162:165], v[82:85], v[154:157], v[162:165]
	v_mfma_f32_16x16x32_bf16 v[142:145], v[62:65], v[174:177], v[142:145]
	v_mfma_f32_16x16x32_bf16 v[138:141], v[82:85], v[174:177], v[138:141]
	v_mfma_f32_16x16x32_bf16 v[118:121], v[62:65], v[182:185], v[118:121]
	v_mfma_f32_16x16x32_bf16 v[114:117], v[82:85], v[182:185], v[114:117]
	v_mfma_f32_16x16x32_bf16 v[94:97], v[62:65], v[190:193], v[94:97]
	v_mfma_f32_16x16x32_bf16 v[90:93], v[82:85], v[190:193], v[90:93]
	v_mfma_f32_16x16x32_bf16 v[158:161], v[102:105], v[150:153], v[158:161]
	v_mfma_f32_16x16x32_bf16 v[146:149], v[122:125], v[150:153], v[146:149]
	v_mfma_f32_16x16x32_bf16 v[134:137], v[102:105], v[170:173], v[134:137]
	v_mfma_f32_16x16x32_bf16 v[130:133], v[122:125], v[170:173], v[130:133]
	v_mfma_f32_16x16x32_bf16 v[110:113], v[102:105], v[178:181], v[110:113]
	v_mfma_f32_16x16x32_bf16 v[98:101], v[122:125], v[178:181], v[98:101]
	v_mfma_f32_16x16x32_bf16 v[86:89], v[102:105], v[186:189], v[86:89]
	v_mfma_f32_16x16x32_bf16 v[74:77], v[122:125], v[186:189], v[74:77]
	v_mfma_f32_16x16x32_bf16 v[158:161], v[106:109], v[154:157], v[158:161]
	v_mfma_f32_16x16x32_bf16 v[154:157], v[126:129], v[154:157], v[146:149]
	v_mfma_f32_16x16x32_bf16 v[134:137], v[106:109], v[174:177], v[134:137]
	v_mfma_f32_16x16x32_bf16 v[130:133], v[126:129], v[174:177], v[130:133]
	v_mfma_f32_16x16x32_bf16 v[110:113], v[106:109], v[182:185], v[110:113]
	v_mfma_f32_16x16x32_bf16 v[98:101], v[126:129], v[182:185], v[98:101]
	v_mfma_f32_16x16x32_bf16 v[86:89], v[106:109], v[190:193], v[86:89]
	v_mfma_f32_16x16x32_bf16 v[74:77], v[126:129], v[190:193], v[74:77]
	s_barrier
	s_add_u32 s98, s44, 0xfff80080
	s_addc_u32 s99, s45, -1
	s_add_i32 s44, s53, s48
	s_mov_b32 m0, s44
	ds_read_b128 v[146:149], v221 offset:49152
	ds_read_b128 v[150:153], v221 offset:50176
	ds_read_b128 v[170:173], v221 offset:51200
	ds_read_b128 v[174:177], v221 offset:52224
	ds_read_b128 v[178:181], v221 offset:53248
	ds_read_b128 v[182:185], v221 offset:54272
	ds_read_b128 v[186:189], v221 offset:55296
	ds_read_b128 v[190:193], v221 offset:56320
	s_add_u32 s100, s42, 0x80
	s_addc_u32 s101, s43, 0
	global_load_lds_dwordx4 v198, s[100:101]
	s_add_i32 m0, s44, 0x2000
	s_add_u32 s42, s42, 0x80080
	s_addc_u32 s43, s43, 0
	s_add_i32 s44, s54, s48
	global_load_lds_dwordx4 v202, s[100:101]
	s_mov_b32 m0, s44
	s_nop 0
	global_load_lds_dwordx4 v198, s[42:43]
	s_add_i32 m0, s44, 0x2000
	s_nop 0
	global_load_lds_dwordx4 v202, s[42:43]
	s_mov_b32 m0, s79
	s_nop 0
	global_load_lds_dwordx4 v196, s[98:99]
	s_mov_b32 m0, s80
	s_nop 0
	global_load_lds_dwordx4 v200, s[98:99]
	s_waitcnt vmcnt(8)
	s_waitcnt lgkmcnt(0)
	s_barrier
	v_mfma_f32_16x16x32_bf16 v[70:73], v[58:61], v[146:149], v[70:73]
	v_mfma_f32_16x16x32_bf16 v[66:69], v[78:81], v[146:149], v[66:69]
	v_mfma_f32_16x16x32_bf16 v[46:49], v[58:61], v[170:173], v[46:49]
	v_mfma_f32_16x16x32_bf16 v[42:45], v[78:81], v[170:173], v[42:45]
	v_mfma_f32_16x16x32_bf16 v[30:33], v[58:61], v[178:181], v[30:33]
	v_mfma_f32_16x16x32_bf16 v[26:29], v[78:81], v[178:181], v[26:29]
	v_mfma_f32_16x16x32_bf16 v[14:17], v[58:61], v[186:189], v[14:17]
	v_mfma_f32_16x16x32_bf16 v[10:13], v[78:81], v[186:189], v[10:13]
	v_mfma_f32_16x16x32_bf16 v[70:73], v[62:65], v[150:153], v[70:73]
	v_mfma_f32_16x16x32_bf16 v[66:69], v[82:85], v[150:153], v[66:69]
	v_mfma_f32_16x16x32_bf16 v[46:49], v[62:65], v[174:177], v[46:49]
	v_mfma_f32_16x16x32_bf16 v[42:45], v[82:85], v[174:177], v[42:45]
	v_mfma_f32_16x16x32_bf16 v[30:33], v[62:65], v[182:185], v[30:33]
	v_mfma_f32_16x16x32_bf16 v[26:29], v[82:85], v[182:185], v[26:29]
	v_mfma_f32_16x16x32_bf16 v[14:17], v[62:65], v[190:193], v[14:17]
	v_mfma_f32_16x16x32_bf16 v[10:13], v[82:85], v[190:193], v[10:13]
	v_mfma_f32_16x16x32_bf16 v[54:57], v[102:105], v[146:149], v[54:57]
	v_mfma_f32_16x16x32_bf16 v[50:53], v[122:125], v[146:149], v[50:53]
	v_mfma_f32_16x16x32_bf16 v[38:41], v[102:105], v[170:173], v[38:41]
	v_mfma_f32_16x16x32_bf16 v[34:37], v[122:125], v[170:173], v[34:37]
	v_mfma_f32_16x16x32_bf16 v[22:25], v[102:105], v[178:181], v[22:25]
	v_mfma_f32_16x16x32_bf16 v[18:21], v[122:125], v[178:181], v[18:21]
	v_mfma_f32_16x16x32_bf16 v[6:9], v[102:105], v[186:189], v[6:9]
	v_mfma_f32_16x16x32_bf16 v[2:5], v[122:125], v[186:189], v[2:5]
	v_mfma_f32_16x16x32_bf16 v[54:57], v[106:109], v[150:153], v[54:57]
	v_mfma_f32_16x16x32_bf16 v[50:53], v[126:129], v[150:153], v[50:53]
	v_mfma_f32_16x16x32_bf16 v[38:41], v[106:109], v[174:177], v[38:41]
	v_mfma_f32_16x16x32_bf16 v[34:37], v[126:129], v[174:177], v[34:37]
	v_mfma_f32_16x16x32_bf16 v[22:25], v[106:109], v[182:185], v[22:25]
	v_mfma_f32_16x16x32_bf16 v[18:21], v[126:129], v[182:185], v[18:21]
	v_mfma_f32_16x16x32_bf16 v[6:9], v[106:109], v[190:193], v[6:9]
	v_mfma_f32_16x16x32_bf16 v[2:5], v[126:129], v[190:193], v[2:5]
	s_barrier
	s_add_i32 s52, s52, 2
	s_add_u32 s46, s46, 0x100
	s_addc_u32 s47, s47, 0
	s_add_u32 s40, s40, 0x100
	s_addc_u32 s41, s41, 0
	s_cmp_gt_u32 s52, 29
	s_cbranch_scc0 .LBB0_176
	s_and_b64 vcc, exec, s[24:25]
	s_cbranch_vccz .LBB0_179
	s_barrier

.LBB0_651:
	ds_read_b128 v[140:143], v197
	ds_read_b128 v[144:147], v197 offset:1024
	ds_read_b128 v[148:151], v197 offset:2048
	ds_read_b128 v[152:155], v197 offset:3072
	ds_read_b128 v[156:159], v198
	ds_read_b128 v[160:163], v198 offset:1024
	ds_read_b128 v[164:167], v198 offset:2048
	ds_read_b128 v[168:171], v198 offset:3072
	s_add_u32 s28, s26, 0xfff80080
	s_addc_u32 s29, s27, -1
	s_cmp_eq_u32 s46, 28
	s_cselect_b32 s31, s15, s29
	s_cselect_b32 s30, s23, s28
	s_cselect_b32 s29, s13, s45
	s_cselect_b32 s28, s43, s44
	s_add_i32 m0, s25, 0xc000
	ds_read_b128 v[172:175], v199
	ds_read_b128 v[176:179], v199 offset:1024
	ds_read_b128 v[180:183], v199 offset:2048
	ds_read_b128 v[184:187], v199 offset:3072
	ds_read_b128 v[188:191], v199 offset:4096
	ds_read_b128 v[202:205], v199 offset:5120
	ds_read_b128 v[206:209], v199 offset:6144
	ds_read_b128 v[210:213], v199 offset:7168
	global_load_lds_dwordx4 v134, s[26:27]
	s_add_i32 m0, s25, 0xe000
	s_nop 0
	global_load_lds_dwordx4 v136, s[26:27]
	s_waitcnt vmcnt(8)
	s_waitcnt lgkmcnt(0)
	s_barrier
	v_mfma_f32_16x16x32_bf16 v[126:129], v[140:143], v[172:175], v[126:129]
	v_mfma_f32_16x16x32_bf16 v[122:125], v[148:151], v[172:175], v[122:125]
	v_mfma_f32_16x16x32_bf16 v[110:113], v[140:143], v[180:183], v[110:113]
	v_mfma_f32_16x16x32_bf16 v[106:109], v[148:151], v[180:183], v[106:109]
	v_mfma_f32_16x16x32_bf16 v[94:97], v[140:143], v[188:191], v[94:97]
	v_mfma_f32_16x16x32_bf16 v[90:93], v[148:151], v[188:191], v[90:93]
	v_mfma_f32_16x16x32_bf16 v[78:81], v[140:143], v[206:209], v[78:81]
	v_mfma_f32_16x16x32_bf16 v[74:77], v[148:151], v[206:209], v[74:77]
	v_mfma_f32_16x16x32_bf16 v[126:129], v[144:147], v[176:179], v[126:129]
	v_mfma_f32_16x16x32_bf16 v[122:125], v[152:155], v[176:179], v[122:125]
	v_mfma_f32_16x16x32_bf16 v[110:113], v[144:147], v[184:187], v[110:113]
	v_mfma_f32_16x16x32_bf16 v[106:109], v[152:155], v[184:187], v[106:109]
	v_mfma_f32_16x16x32_bf16 v[94:97], v[144:147], v[202:205], v[94:97]
	v_mfma_f32_16x16x32_bf16 v[90:93], v[152:155], v[202:205], v[90:93]
	v_mfma_f32_16x16x32_bf16 v[78:81], v[144:147], v[210:213], v[78:81]
	v_mfma_f32_16x16x32_bf16 v[74:77], v[152:155], v[210:213], v[74:77]
	v_mfma_f32_16x16x32_bf16 v[118:121], v[156:159], v[172:175], v[118:121]
	v_mfma_f32_16x16x32_bf16 v[114:117], v[164:167], v[172:175], v[114:117]
	v_mfma_f32_16x16x32_bf16 v[102:105], v[156:159], v[180:183], v[102:105]
	v_mfma_f32_16x16x32_bf16 v[98:101], v[164:167], v[180:183], v[98:101]
	v_mfma_f32_16x16x32_bf16 v[86:89], v[156:159], v[188:191], v[86:89]
	v_mfma_f32_16x16x32_bf16 v[82:85], v[164:167], v[188:191], v[82:85]
	v_mfma_f32_16x16x32_bf16 v[70:73], v[156:159], v[206:209], v[70:73]
	v_mfma_f32_16x16x32_bf16 v[66:69], v[164:167], v[206:209], v[66:69]
	v_mfma_f32_16x16x32_bf16 v[118:121], v[160:163], v[176:179], v[118:121]
	v_mfma_f32_16x16x32_bf16 v[114:117], v[168:171], v[176:179], v[114:117]
	v_mfma_f32_16x16x32_bf16 v[102:105], v[160:163], v[184:187], v[102:105]
	v_mfma_f32_16x16x32_bf16 v[98:101], v[168:171], v[184:187], v[98:101]
	v_mfma_f32_16x16x32_bf16 v[86:89], v[160:163], v[202:205], v[86:89]
	v_mfma_f32_16x16x32_bf16 v[82:85], v[168:171], v[202:205], v[82:85]
	v_mfma_f32_16x16x32_bf16 v[70:73], v[160:163], v[210:213], v[70:73]
	v_mfma_f32_16x16x32_bf16 v[66:69], v[168:171], v[210:213], v[66:69]
	s_barrier
	s_add_i32 s47, s2, s3
	s_mov_b32 m0, s47
	ds_read_b128 v[172:175], v199 offset:16384
	ds_read_b128 v[176:179], v199 offset:17408
	ds_read_b128 v[180:183], v199 offset:18432
	ds_read_b128 v[184:187], v199 offset:19456
	ds_read_b128 v[188:191], v199 offset:20480
	ds_read_b128 v[202:205], v199 offset:21504
	ds_read_b128 v[206:209], v199 offset:22528
	ds_read_b128 v[210:213], v199 offset:23552
	global_load_lds_dwordx4 v130, s[28:29]
	s_add_i32 m0, s47, 0x2000
	s_add_u32 s48, s28, 0x80000
	s_addc_u32 s49, s29, 0
	s_add_i32 s47, s42, s3
	global_load_lds_dwordx4 v132, s[28:29]
	s_mov_b32 m0, s47
	s_nop 0
	global_load_lds_dwordx4 v130, s[48:49]
	s_add_i32 m0, s47, 0x2000
	s_nop 0
	global_load_lds_dwordx4 v132, s[48:49]
	s_mov_b32 m0, s25
	s_nop 0
	global_load_lds_dwordx4 v130, s[30:31]
	s_mov_b32 m0, s34
	s_nop 0
	global_load_lds_dwordx4 v132, s[30:31]
	s_waitcnt vmcnt(8)
	s_waitcnt lgkmcnt(0)
	s_barrier
	v_mfma_f32_16x16x32_bf16 v[62:65], v[140:143], v[172:175], v[62:65]
	v_mfma_f32_16x16x32_bf16 v[58:61], v[148:151], v[172:175], v[58:61]
	v_mfma_f32_16x16x32_bf16 v[46:49], v[140:143], v[180:183], v[46:49]
	v_mfma_f32_16x16x32_bf16 v[42:45], v[148:151], v[180:183], v[42:45]
	v_mfma_f32_16x16x32_bf16 v[30:33], v[140:143], v[188:191], v[30:33]
	v_mfma_f32_16x16x32_bf16 v[26:29], v[148:151], v[188:191], v[26:29]
	v_mfma_f32_16x16x32_bf16 v[14:17], v[140:143], v[206:209], v[14:17]
	v_mfma_f32_16x16x32_bf16 v[10:13], v[148:151], v[206:209], v[10:13]
	v_mfma_f32_16x16x32_bf16 v[62:65], v[144:147], v[176:179], v[62:65]
	v_mfma_f32_16x16x32_bf16 v[58:61], v[152:155], v[176:179], v[58:61]
	v_mfma_f32_16x16x32_bf16 v[46:49], v[144:147], v[184:187], v[46:49]
	v_mfma_f32_16x16x32_bf16 v[42:45], v[152:155], v[184:187], v[42:45]
	v_mfma_f32_16x16x32_bf16 v[30:33], v[144:147], v[202:205], v[30:33]
	v_mfma_f32_16x16x32_bf16 v[26:29], v[152:155], v[202:205], v[26:29]
	v_mfma_f32_16x16x32_bf16 v[14:17], v[144:147], v[210:213], v[14:17]
	v_mfma_f32_16x16x32_bf16 v[10:13], v[152:155], v[210:213], v[10:13]
	v_mfma_f32_16x16x32_bf16 v[54:57], v[156:159], v[172:175], v[54:57]
	v_mfma_f32_16x16x32_bf16 v[50:53], v[164:167], v[172:175], v[50:53]
	v_mfma_f32_16x16x32_bf16 v[38:41], v[156:159], v[180:183], v[38:41]
	v_mfma_f32_16x16x32_bf16 v[34:37], v[164:167], v[180:183], v[34:37]
	v_mfma_f32_16x16x32_bf16 v[22:25], v[156:159], v[188:191], v[22:25]
	v_mfma_f32_16x16x32_bf16 v[18:21], v[164:167], v[188:191], v[18:21]
	v_mfma_f32_16x16x32_bf16 v[6:9], v[156:159], v[206:209], v[6:9]
	v_mfma_f32_16x16x32_bf16 v[2:5], v[164:167], v[206:209], v[2:5]
	v_mfma_f32_16x16x32_bf16 v[54:57], v[160:163], v[176:179], v[54:57]
	v_mfma_f32_16x16x32_bf16 v[50:53], v[168:171], v[176:179], v[50:53]
	v_mfma_f32_16x16x32_bf16 v[38:41], v[160:163], v[184:187], v[38:41]
	v_mfma_f32_16x16x32_bf16 v[34:37], v[168:171], v[184:187], v[34:37]
	v_mfma_f32_16x16x32_bf16 v[22:25], v[160:163], v[202:205], v[22:25]
	v_mfma_f32_16x16x32_bf16 v[18:21], v[168:171], v[202:205], v[18:21]
	v_mfma_f32_16x16x32_bf16 v[6:9], v[160:163], v[210:213], v[6:9]
	v_mfma_f32_16x16x32_bf16 v[2:5], v[168:171], v[210:213], v[2:5]
	s_barrier
	s_add_i32 s47, 0, 0x18000
	s_add_i32 s48, 0, 0x1c000
	v_add_u32_e32 v152, s47, v195
	v_add_u32_e32 v168, s48, v195
	ds_read_b128 v[140:143], v152
	ds_read_b128 v[144:147], v152 offset:1024
	ds_read_b128 v[148:151], v152 offset:2048
	ds_read_b128 v[152:155], v152 offset:3072
	ds_read_b128 v[156:159], v168
	ds_read_b128 v[160:163], v168 offset:1024
	ds_read_b128 v[164:167], v168 offset:2048
	ds_read_b128 v[168:171], v168 offset:3072
	s_add_u32 s30, s30, 0x80000
	s_addc_u32 s31, s31, 0
	s_mov_b32 m0, s35
	ds_read_b128 v[172:175], v199 offset:32768
	ds_read_b128 v[176:179], v199 offset:33792
	ds_read_b128 v[180:183], v199 offset:34816
	ds_read_b128 v[184:187], v199 offset:35840
	ds_read_b128 v[188:191], v199 offset:36864
	ds_read_b128 v[202:205], v199 offset:37888
	ds_read_b128 v[206:209], v199 offset:38912
	ds_read_b128 v[210:213], v199 offset:39936
	global_load_lds_dwordx4 v130, s[30:31]
	s_mov_b32 m0, s36
	s_nop 0
	global_load_lds_dwordx4 v132, s[30:31]
	s_waitcnt vmcnt(8)
	s_waitcnt lgkmcnt(0)
	s_barrier
	v_mfma_f32_16x16x32_bf16 v[126:129], v[140:143], v[172:175], v[126:129]
	v_mfma_f32_16x16x32_bf16 v[122:125], v[148:151], v[172:175], v[122:125]
	v_mfma_f32_16x16x32_bf16 v[110:113], v[140:143], v[180:183], v[110:113]
	v_mfma_f32_16x16x32_bf16 v[106:109], v[148:151], v[180:183], v[106:109]
	v_mfma_f32_16x16x32_bf16 v[94:97], v[140:143], v[188:191], v[94:97]
	v_mfma_f32_16x16x32_bf16 v[90:93], v[148:151], v[188:191], v[90:93]
	v_mfma_f32_16x16x32_bf16 v[78:81], v[140:143], v[206:209], v[78:81]
	v_mfma_f32_16x16x32_bf16 v[74:77], v[148:151], v[206:209], v[74:77]
	v_mfma_f32_16x16x32_bf16 v[126:129], v[144:147], v[176:179], v[126:129]
	v_mfma_f32_16x16x32_bf16 v[122:125], v[152:155], v[176:179], v[122:125]
	v_mfma_f32_16x16x32_bf16 v[110:113], v[144:147], v[184:187], v[110:113]
	v_mfma_f32_16x16x32_bf16 v[106:109], v[152:155], v[184:187], v[106:109]
	v_mfma_f32_16x16x32_bf16 v[94:97], v[144:147], v[202:205], v[94:97]
	v_mfma_f32_16x16x32_bf16 v[90:93], v[152:155], v[202:205], v[90:93]
	v_mfma_f32_16x16x32_bf16 v[78:81], v[144:147], v[210:213], v[78:81]
	v_mfma_f32_16x16x32_bf16 v[74:77], v[152:155], v[210:213], v[74:77]
	v_mfma_f32_16x16x32_bf16 v[118:121], v[156:159], v[172:175], v[118:121]
	v_mfma_f32_16x16x32_bf16 v[114:117], v[164:167], v[172:175], v[114:117]
	v_mfma_f32_16x16x32_bf16 v[102:105], v[156:159], v[180:183], v[102:105]
	v_mfma_f32_16x16x32_bf16 v[98:101], v[164:167], v[180:183], v[98:101]
	v_mfma_f32_16x16x32_bf16 v[86:89], v[156:159], v[188:191], v[86:89]
	v_mfma_f32_16x16x32_bf16 v[82:85], v[164:167], v[188:191], v[82:85]
	v_mfma_f32_16x16x32_bf16 v[70:73], v[156:159], v[206:209], v[70:73]
	v_mfma_f32_16x16x32_bf16 v[66:69], v[164:167], v[206:209], v[66:69]
	v_mfma_f32_16x16x32_bf16 v[118:121], v[160:163], v[176:179], v[118:121]
	v_mfma_f32_16x16x32_bf16 v[114:117], v[168:171], v[176:179], v[114:117]
	v_mfma_f32_16x16x32_bf16 v[102:105], v[160:163], v[184:187], v[102:105]
	v_mfma_f32_16x16x32_bf16 v[98:101], v[168:171], v[184:187], v[98:101]
	v_mfma_f32_16x16x32_bf16 v[86:89], v[160:163], v[202:205], v[86:89]
	v_mfma_f32_16x16x32_bf16 v[82:85], v[168:171], v[202:205], v[82:85]
	v_mfma_f32_16x16x32_bf16 v[70:73], v[160:163], v[210:213], v[70:73]
	v_mfma_f32_16x16x32_bf16 v[66:69], v[168:171], v[210:213], v[66:69]
	s_barrier
	s_add_u32 s98, s30, 0xfff80080
	s_addc_u32 s99, s31, -1
	s_add_i32 s30, s47, s3
	s_mov_b32 m0, s30
	ds_read_b128 v[172:175], v199 offset:49152
	ds_read_b128 v[176:179], v199 offset:50176
	ds_read_b128 v[180:183], v199 offset:51200
	ds_read_b128 v[184:187], v199 offset:52224
	ds_read_b128 v[188:191], v199 offset:53248
	ds_read_b128 v[202:205], v199 offset:54272
	ds_read_b128 v[206:209], v199 offset:55296
	ds_read_b128 v[210:213], v199 offset:56320
	s_add_u32 s100, s28, 0x80
	s_addc_u32 s101, s29, 0
	global_load_lds_dwordx4 v130, s[100:101]
	s_add_i32 m0, s30, 0x2000
	s_add_u32 s28, s28, 0x80080
	s_addc_u32 s29, s29, 0
	s_add_i32 s30, s48, s3
	global_load_lds_dwordx4 v132, s[100:101]
	s_mov_b32 m0, s30
	s_nop 0
	global_load_lds_dwordx4 v130, s[28:29]
	s_add_i32 m0, s30, 0x2000
	s_nop 0
	global_load_lds_dwordx4 v132, s[28:29]
	s_mov_b32 m0, s38
	s_nop 0
	global_load_lds_dwordx4 v130, s[98:99]
	s_mov_b32 m0, s39
	s_nop 0
	global_load_lds_dwordx4 v132, s[98:99]
	s_waitcnt vmcnt(8)
	s_waitcnt lgkmcnt(0)
	s_barrier
	v_mfma_f32_16x16x32_bf16 v[62:65], v[140:143], v[172:175], v[62:65]
	v_mfma_f32_16x16x32_bf16 v[58:61], v[148:151], v[172:175], v[58:61]
	v_mfma_f32_16x16x32_bf16 v[46:49], v[140:143], v[180:183], v[46:49]
	v_mfma_f32_16x16x32_bf16 v[42:45], v[148:151], v[180:183], v[42:45]
	v_mfma_f32_16x16x32_bf16 v[30:33], v[140:143], v[188:191], v[30:33]
	v_mfma_f32_16x16x32_bf16 v[26:29], v[148:151], v[188:191], v[26:29]
	v_mfma_f32_16x16x32_bf16 v[14:17], v[140:143], v[206:209], v[14:17]
	v_mfma_f32_16x16x32_bf16 v[10:13], v[148:151], v[206:209], v[10:13]
	v_mfma_f32_16x16x32_bf16 v[62:65], v[144:147], v[176:179], v[62:65]
	v_mfma_f32_16x16x32_bf16 v[58:61], v[152:155], v[176:179], v[58:61]
	v_mfma_f32_16x16x32_bf16 v[46:49], v[144:147], v[184:187], v[46:49]
	v_mfma_f32_16x16x32_bf16 v[42:45], v[152:155], v[184:187], v[42:45]
	v_mfma_f32_16x16x32_bf16 v[30:33], v[144:147], v[202:205], v[30:33]
	v_mfma_f32_16x16x32_bf16 v[26:29], v[152:155], v[202:205], v[26:29]
	v_mfma_f32_16x16x32_bf16 v[14:17], v[144:147], v[210:213], v[14:17]
	v_mfma_f32_16x16x32_bf16 v[10:13], v[152:155], v[210:213], v[10:13]
	v_mfma_f32_16x16x32_bf16 v[54:57], v[156:159], v[172:175], v[54:57]
	v_mfma_f32_16x16x32_bf16 v[50:53], v[164:167], v[172:175], v[50:53]
	v_mfma_f32_16x16x32_bf16 v[38:41], v[156:159], v[180:183], v[38:41]
	v_mfma_f32_16x16x32_bf16 v[34:37], v[164:167], v[180:183], v[34:37]
	v_mfma_f32_16x16x32_bf16 v[22:25], v[156:159], v[188:191], v[22:25]
	v_mfma_f32_16x16x32_bf16 v[18:21], v[164:167], v[188:191], v[18:21]
	v_mfma_f32_16x16x32_bf16 v[6:9], v[156:159], v[206:209], v[6:9]
	v_mfma_f32_16x16x32_bf16 v[2:5], v[164:167], v[206:209], v[2:5]
	v_mfma_f32_16x16x32_bf16 v[54:57], v[160:163], v[176:179], v[54:57]
	v_mfma_f32_16x16x32_bf16 v[50:53], v[168:171], v[176:179], v[50:53]
	v_mfma_f32_16x16x32_bf16 v[38:41], v[160:163], v[184:187], v[38:41]
	v_mfma_f32_16x16x32_bf16 v[34:37], v[168:171], v[184:187], v[34:37]
	v_mfma_f32_16x16x32_bf16 v[22:25], v[160:163], v[202:205], v[22:25]
	v_mfma_f32_16x16x32_bf16 v[18:21], v[168:171], v[202:205], v[18:21]
	v_mfma_f32_16x16x32_bf16 v[6:9], v[160:163], v[210:213], v[6:9]
	v_mfma_f32_16x16x32_bf16 v[2:5], v[168:171], v[210:213], v[2:5]
	s_barrier
	s_add_i32 s46, s46, 2
	s_add_u32 s44, s44, 0x100
	s_addc_u32 s45, s45, 0
	s_add_u32 s26, s26, 0x100
	s_addc_u32 s27, s27, 0
	s_cmp_gt_u32 s46, 29
	s_cbranch_scc0 .LBB0_651
	s_and_b64 vcc, exec, s[10:11]
	s_cbranch_vccz .LBB0_654
	s_barrier

.LBB0_808:
	ds_read_b128 v[144:147], v152
	ds_read_b128 v[156:159], v152 offset:1024
	ds_read_b128 v[160:163], v152 offset:2048
	ds_read_b128 v[164:167], v152 offset:3072
	ds_read_b128 v[168:171], v153
	ds_read_b128 v[172:175], v153 offset:1024
	ds_read_b128 v[176:179], v153 offset:2048
	ds_read_b128 v[180:183], v153 offset:3072
	s_add_u32 s34, s30, 0xfff80080
	s_addc_u32 s35, s31, -1
	s_cmp_eq_u32 s55, 28
	s_cselect_b32 s37, s19, s35
	s_cselect_b32 s36, s51, s34
	s_cselect_b32 s35, s17, s54
	s_cselect_b32 s34, s52, s53
	s_add_i32 m0, s27, 0xc000
	ds_read_b128 v[184:187], v154
	ds_read_b128 v[188:191], v154 offset:1024
	ds_read_b128 v[196:199], v154 offset:2048
	ds_read_b128 v[200:203], v154 offset:3072
	ds_read_b128 v[204:207], v154 offset:4096
	ds_read_b128 v[208:211], v154 offset:5120
	ds_read_b128 v[212:215], v154 offset:6144
	ds_read_b128 v[216:219], v154 offset:7168
	global_load_lds_dwordx4 v138, s[30:31]
	s_add_i32 m0, s27, 0xe000
	s_nop 0
	global_load_lds_dwordx4 v140, s[30:31]
	s_waitcnt vmcnt(8)
	s_waitcnt lgkmcnt(0)
	s_barrier
	v_mfma_f32_16x16x32_bf16 v[126:129], v[144:147], v[184:187], v[126:129]
	v_mfma_f32_16x16x32_bf16 v[122:125], v[160:163], v[184:187], v[122:125]
	v_mfma_f32_16x16x32_bf16 v[110:113], v[144:147], v[196:199], v[110:113]
	v_mfma_f32_16x16x32_bf16 v[106:109], v[160:163], v[196:199], v[106:109]
	v_mfma_f32_16x16x32_bf16 v[94:97], v[144:147], v[204:207], v[94:97]
	v_mfma_f32_16x16x32_bf16 v[90:93], v[160:163], v[204:207], v[90:93]
	v_mfma_f32_16x16x32_bf16 v[78:81], v[144:147], v[212:215], v[78:81]
	v_mfma_f32_16x16x32_bf16 v[74:77], v[160:163], v[212:215], v[74:77]
	v_mfma_f32_16x16x32_bf16 v[126:129], v[156:159], v[188:191], v[126:129]
	v_mfma_f32_16x16x32_bf16 v[122:125], v[164:167], v[188:191], v[122:125]
	v_mfma_f32_16x16x32_bf16 v[110:113], v[156:159], v[200:203], v[110:113]
	v_mfma_f32_16x16x32_bf16 v[106:109], v[164:167], v[200:203], v[106:109]
	v_mfma_f32_16x16x32_bf16 v[94:97], v[156:159], v[208:211], v[94:97]
	v_mfma_f32_16x16x32_bf16 v[90:93], v[164:167], v[208:211], v[90:93]
	v_mfma_f32_16x16x32_bf16 v[78:81], v[156:159], v[216:219], v[78:81]
	v_mfma_f32_16x16x32_bf16 v[74:77], v[164:167], v[216:219], v[74:77]
	v_mfma_f32_16x16x32_bf16 v[118:121], v[168:171], v[184:187], v[118:121]
	v_mfma_f32_16x16x32_bf16 v[114:117], v[176:179], v[184:187], v[114:117]
	v_mfma_f32_16x16x32_bf16 v[102:105], v[168:171], v[196:199], v[102:105]
	v_mfma_f32_16x16x32_bf16 v[98:101], v[176:179], v[196:199], v[98:101]
	v_mfma_f32_16x16x32_bf16 v[86:89], v[168:171], v[204:207], v[86:89]
	v_mfma_f32_16x16x32_bf16 v[82:85], v[176:179], v[204:207], v[82:85]
	v_mfma_f32_16x16x32_bf16 v[70:73], v[168:171], v[212:215], v[70:73]
	v_mfma_f32_16x16x32_bf16 v[66:69], v[176:179], v[212:215], v[66:69]
	v_mfma_f32_16x16x32_bf16 v[118:121], v[172:175], v[188:191], v[118:121]
	v_mfma_f32_16x16x32_bf16 v[114:117], v[180:183], v[188:191], v[114:117]
	v_mfma_f32_16x16x32_bf16 v[102:105], v[172:175], v[200:203], v[102:105]
	v_mfma_f32_16x16x32_bf16 v[98:101], v[180:183], v[200:203], v[98:101]
	v_mfma_f32_16x16x32_bf16 v[86:89], v[172:175], v[208:211], v[86:89]
	v_mfma_f32_16x16x32_bf16 v[82:85], v[180:183], v[208:211], v[82:85]
	v_mfma_f32_16x16x32_bf16 v[70:73], v[172:175], v[216:219], v[70:73]
	v_mfma_f32_16x16x32_bf16 v[66:69], v[180:183], v[216:219], v[66:69]
	s_barrier
	s_add_i32 s56, s47, s38
	s_mov_b32 m0, s56
	ds_read_b128 v[184:187], v154 offset:16384
	ds_read_b128 v[188:191], v154 offset:17408
	ds_read_b128 v[196:199], v154 offset:18432
	ds_read_b128 v[200:203], v154 offset:19456
	ds_read_b128 v[204:207], v154 offset:20480
	ds_read_b128 v[208:211], v154 offset:21504
	ds_read_b128 v[212:215], v154 offset:22528
	ds_read_b128 v[216:219], v154 offset:23552
	global_load_lds_dwordx4 v132, s[34:35]
	s_add_i32 m0, s56, 0x2000
	s_add_u32 s56, s34, 0x80000
	s_addc_u32 s57, s35, 0
	s_add_i32 s58, s48, s38
	global_load_lds_dwordx4 v136, s[34:35]
	s_mov_b32 m0, s58
	s_nop 0
	global_load_lds_dwordx4 v132, s[56:57]
	s_add_i32 m0, s58, 0x2000
	s_nop 0
	global_load_lds_dwordx4 v136, s[56:57]
	s_mov_b32 m0, s27
	s_nop 0
	global_load_lds_dwordx4 v130, s[36:37]
	s_mov_b32 m0, s29
	s_nop 0
	global_load_lds_dwordx4 v134, s[36:37]
	s_waitcnt vmcnt(8)
	s_waitcnt lgkmcnt(0)
	s_barrier
	v_mfma_f32_16x16x32_bf16 v[62:65], v[144:147], v[184:187], v[62:65]
	v_mfma_f32_16x16x32_bf16 v[58:61], v[160:163], v[184:187], v[58:61]
	v_mfma_f32_16x16x32_bf16 v[46:49], v[144:147], v[196:199], v[46:49]
	v_mfma_f32_16x16x32_bf16 v[42:45], v[160:163], v[196:199], v[42:45]
	v_mfma_f32_16x16x32_bf16 v[30:33], v[144:147], v[204:207], v[30:33]
	v_mfma_f32_16x16x32_bf16 v[26:29], v[160:163], v[204:207], v[26:29]
	v_mfma_f32_16x16x32_bf16 v[14:17], v[144:147], v[212:215], v[14:17]
	v_mfma_f32_16x16x32_bf16 v[10:13], v[160:163], v[212:215], v[10:13]
	v_mfma_f32_16x16x32_bf16 v[62:65], v[156:159], v[188:191], v[62:65]
	v_mfma_f32_16x16x32_bf16 v[58:61], v[164:167], v[188:191], v[58:61]
	v_mfma_f32_16x16x32_bf16 v[46:49], v[156:159], v[200:203], v[46:49]
	v_mfma_f32_16x16x32_bf16 v[42:45], v[164:167], v[200:203], v[42:45]
	v_mfma_f32_16x16x32_bf16 v[30:33], v[156:159], v[208:211], v[30:33]
	v_mfma_f32_16x16x32_bf16 v[26:29], v[164:167], v[208:211], v[26:29]
	v_mfma_f32_16x16x32_bf16 v[14:17], v[156:159], v[216:219], v[14:17]
	v_mfma_f32_16x16x32_bf16 v[10:13], v[164:167], v[216:219], v[10:13]
	v_mfma_f32_16x16x32_bf16 v[54:57], v[168:171], v[184:187], v[54:57]
	v_mfma_f32_16x16x32_bf16 v[50:53], v[176:179], v[184:187], v[50:53]
	v_mfma_f32_16x16x32_bf16 v[38:41], v[168:171], v[196:199], v[38:41]
	v_mfma_f32_16x16x32_bf16 v[34:37], v[176:179], v[196:199], v[34:37]
	v_mfma_f32_16x16x32_bf16 v[22:25], v[168:171], v[204:207], v[22:25]
	v_mfma_f32_16x16x32_bf16 v[18:21], v[176:179], v[204:207], v[18:21]
	v_mfma_f32_16x16x32_bf16 v[6:9], v[168:171], v[212:215], v[6:9]
	v_mfma_f32_16x16x32_bf16 v[2:5], v[176:179], v[212:215], v[2:5]
	v_mfma_f32_16x16x32_bf16 v[54:57], v[172:175], v[188:191], v[54:57]
	v_mfma_f32_16x16x32_bf16 v[50:53], v[180:183], v[188:191], v[50:53]
	v_mfma_f32_16x16x32_bf16 v[38:41], v[172:175], v[200:203], v[38:41]
	v_mfma_f32_16x16x32_bf16 v[34:37], v[180:183], v[200:203], v[34:37]
	v_mfma_f32_16x16x32_bf16 v[22:25], v[172:175], v[208:211], v[22:25]
	v_mfma_f32_16x16x32_bf16 v[18:21], v[180:183], v[208:211], v[18:21]
	v_mfma_f32_16x16x32_bf16 v[6:9], v[172:175], v[216:219], v[6:9]
	v_mfma_f32_16x16x32_bf16 v[2:5], v[180:183], v[216:219], v[2:5]
	s_barrier
	s_add_i32 s56, 0, 0x18000
	v_add_u32_e32 v155, s56, v150
	s_add_i32 s57, 0, 0x1c000
	ds_read_b128 v[144:147], v155
	ds_read_b128 v[156:159], v155 offset:1024
	ds_read_b128 v[160:163], v155 offset:2048
	ds_read_b128 v[164:167], v155 offset:3072
	v_add_u32_e32 v155, s57, v150
	ds_read_b128 v[168:171], v155
	ds_read_b128 v[172:175], v155 offset:1024
	ds_read_b128 v[176:179], v155 offset:2048
	ds_read_b128 v[180:183], v155 offset:3072
	s_add_u32 s36, s36, 0x80000
	s_addc_u32 s37, s37, 0
	s_mov_b32 m0, s39
	ds_read_b128 v[184:187], v154 offset:32768
	ds_read_b128 v[188:191], v154 offset:33792
	ds_read_b128 v[196:199], v154 offset:34816
	ds_read_b128 v[200:203], v154 offset:35840
	ds_read_b128 v[204:207], v154 offset:36864
	ds_read_b128 v[208:211], v154 offset:37888
	ds_read_b128 v[212:215], v154 offset:38912
	ds_read_b128 v[216:219], v154 offset:39936
	global_load_lds_dwordx4 v130, s[36:37]
	s_mov_b32 m0, s40
	s_nop 0
	global_load_lds_dwordx4 v134, s[36:37]
	s_waitcnt vmcnt(8)
	s_waitcnt lgkmcnt(0)
	s_barrier
	v_mfma_f32_16x16x32_bf16 v[126:129], v[144:147], v[184:187], v[126:129]
	v_mfma_f32_16x16x32_bf16 v[122:125], v[160:163], v[184:187], v[122:125]
	v_mfma_f32_16x16x32_bf16 v[110:113], v[144:147], v[196:199], v[110:113]
	v_mfma_f32_16x16x32_bf16 v[106:109], v[160:163], v[196:199], v[106:109]
	v_mfma_f32_16x16x32_bf16 v[94:97], v[144:147], v[204:207], v[94:97]
	v_mfma_f32_16x16x32_bf16 v[90:93], v[160:163], v[204:207], v[90:93]
	v_mfma_f32_16x16x32_bf16 v[78:81], v[144:147], v[212:215], v[78:81]
	v_mfma_f32_16x16x32_bf16 v[74:77], v[160:163], v[212:215], v[74:77]
	v_mfma_f32_16x16x32_bf16 v[126:129], v[156:159], v[188:191], v[126:129]
	v_mfma_f32_16x16x32_bf16 v[122:125], v[164:167], v[188:191], v[122:125]
	v_mfma_f32_16x16x32_bf16 v[110:113], v[156:159], v[200:203], v[110:113]
	v_mfma_f32_16x16x32_bf16 v[106:109], v[164:167], v[200:203], v[106:109]
	v_mfma_f32_16x16x32_bf16 v[94:97], v[156:159], v[208:211], v[94:97]
	v_mfma_f32_16x16x32_bf16 v[90:93], v[164:167], v[208:211], v[90:93]
	v_mfma_f32_16x16x32_bf16 v[78:81], v[156:159], v[216:219], v[78:81]
	v_mfma_f32_16x16x32_bf16 v[74:77], v[164:167], v[216:219], v[74:77]
	v_mfma_f32_16x16x32_bf16 v[118:121], v[168:171], v[184:187], v[118:121]
	v_mfma_f32_16x16x32_bf16 v[114:117], v[176:179], v[184:187], v[114:117]
	v_mfma_f32_16x16x32_bf16 v[102:105], v[168:171], v[196:199], v[102:105]
	v_mfma_f32_16x16x32_bf16 v[98:101], v[176:179], v[196:199], v[98:101]
	v_mfma_f32_16x16x32_bf16 v[86:89], v[168:171], v[204:207], v[86:89]
	v_mfma_f32_16x16x32_bf16 v[82:85], v[176:179], v[204:207], v[82:85]
	v_mfma_f32_16x16x32_bf16 v[70:73], v[168:171], v[212:215], v[70:73]
	v_mfma_f32_16x16x32_bf16 v[66:69], v[176:179], v[212:215], v[66:69]
	v_mfma_f32_16x16x32_bf16 v[118:121], v[172:175], v[188:191], v[118:121]
	v_mfma_f32_16x16x32_bf16 v[114:117], v[180:183], v[188:191], v[114:117]
	v_mfma_f32_16x16x32_bf16 v[102:105], v[172:175], v[200:203], v[102:105]
	v_mfma_f32_16x16x32_bf16 v[98:101], v[180:183], v[200:203], v[98:101]
	v_mfma_f32_16x16x32_bf16 v[86:89], v[172:175], v[208:211], v[86:89]
	v_mfma_f32_16x16x32_bf16 v[82:85], v[180:183], v[208:211], v[82:85]
	v_mfma_f32_16x16x32_bf16 v[70:73], v[172:175], v[216:219], v[70:73]
	v_mfma_f32_16x16x32_bf16 v[66:69], v[180:183], v[216:219], v[66:69]
	s_barrier
	s_add_u32 s98, s36, 0xfff80080
	s_addc_u32 s99, s37, -1
	s_add_i32 s36, s56, s38
	s_mov_b32 m0, s36
	ds_read_b128 v[184:187], v154 offset:49152
	ds_read_b128 v[188:191], v154 offset:50176
	ds_read_b128 v[196:199], v154 offset:51200
	ds_read_b128 v[200:203], v154 offset:52224
	ds_read_b128 v[204:207], v154 offset:53248
	ds_read_b128 v[208:211], v154 offset:54272
	ds_read_b128 v[212:215], v154 offset:55296
	ds_read_b128 v[216:219], v154 offset:56320
	s_add_u32 s100, s34, 0x80
	s_addc_u32 s101, s35, 0
	global_load_lds_dwordx4 v132, s[100:101]
	s_add_i32 m0, s36, 0x2000
	s_add_u32 s34, s34, 0x80080
	s_addc_u32 s35, s35, 0
	s_add_i32 s36, s57, s38
	global_load_lds_dwordx4 v136, s[100:101]
	s_mov_b32 m0, s36
	s_nop 0
	global_load_lds_dwordx4 v132, s[34:35]
	s_add_i32 m0, s36, 0x2000
	s_nop 0
	global_load_lds_dwordx4 v136, s[34:35]
	s_mov_b32 m0, s42
	s_nop 0
	global_load_lds_dwordx4 v130, s[98:99]
	s_mov_b32 m0, s43
	s_nop 0
	global_load_lds_dwordx4 v134, s[98:99]
	s_waitcnt vmcnt(8)
	s_waitcnt lgkmcnt(0)
	s_barrier
	v_mfma_f32_16x16x32_bf16 v[62:65], v[144:147], v[184:187], v[62:65]
	v_mfma_f32_16x16x32_bf16 v[58:61], v[160:163], v[184:187], v[58:61]
	v_mfma_f32_16x16x32_bf16 v[46:49], v[144:147], v[196:199], v[46:49]
	v_mfma_f32_16x16x32_bf16 v[42:45], v[160:163], v[196:199], v[42:45]
	v_mfma_f32_16x16x32_bf16 v[30:33], v[144:147], v[204:207], v[30:33]
	v_mfma_f32_16x16x32_bf16 v[26:29], v[160:163], v[204:207], v[26:29]
	v_mfma_f32_16x16x32_bf16 v[14:17], v[144:147], v[212:215], v[14:17]
	v_mfma_f32_16x16x32_bf16 v[10:13], v[160:163], v[212:215], v[10:13]
	v_mfma_f32_16x16x32_bf16 v[62:65], v[156:159], v[188:191], v[62:65]
	v_mfma_f32_16x16x32_bf16 v[58:61], v[164:167], v[188:191], v[58:61]
	v_mfma_f32_16x16x32_bf16 v[46:49], v[156:159], v[200:203], v[46:49]
	v_mfma_f32_16x16x32_bf16 v[42:45], v[164:167], v[200:203], v[42:45]
	v_mfma_f32_16x16x32_bf16 v[30:33], v[156:159], v[208:211], v[30:33]
	v_mfma_f32_16x16x32_bf16 v[26:29], v[164:167], v[208:211], v[26:29]
	v_mfma_f32_16x16x32_bf16 v[14:17], v[156:159], v[216:219], v[14:17]
	v_mfma_f32_16x16x32_bf16 v[10:13], v[164:167], v[216:219], v[10:13]
	v_mfma_f32_16x16x32_bf16 v[54:57], v[168:171], v[184:187], v[54:57]
	v_mfma_f32_16x16x32_bf16 v[50:53], v[176:179], v[184:187], v[50:53]
	v_mfma_f32_16x16x32_bf16 v[38:41], v[168:171], v[196:199], v[38:41]
	v_mfma_f32_16x16x32_bf16 v[34:37], v[176:179], v[196:199], v[34:37]
	v_mfma_f32_16x16x32_bf16 v[22:25], v[168:171], v[204:207], v[22:25]
	v_mfma_f32_16x16x32_bf16 v[18:21], v[176:179], v[204:207], v[18:21]
	v_mfma_f32_16x16x32_bf16 v[6:9], v[168:171], v[212:215], v[6:9]
	v_mfma_f32_16x16x32_bf16 v[2:5], v[176:179], v[212:215], v[2:5]
	v_mfma_f32_16x16x32_bf16 v[54:57], v[172:175], v[188:191], v[54:57]
	v_mfma_f32_16x16x32_bf16 v[50:53], v[180:183], v[188:191], v[50:53]
	v_mfma_f32_16x16x32_bf16 v[38:41], v[172:175], v[200:203], v[38:41]
	v_mfma_f32_16x16x32_bf16 v[34:37], v[180:183], v[200:203], v[34:37]
	v_mfma_f32_16x16x32_bf16 v[22:25], v[172:175], v[208:211], v[22:25]
	v_mfma_f32_16x16x32_bf16 v[18:21], v[180:183], v[208:211], v[18:21]
	v_mfma_f32_16x16x32_bf16 v[6:9], v[172:175], v[216:219], v[6:9]
	v_mfma_f32_16x16x32_bf16 v[2:5], v[180:183], v[216:219], v[2:5]
	s_barrier
	s_add_i32 s55, s55, 2
	s_add_u32 s53, s53, 0x100
	s_addc_u32 s54, s54, 0
	s_add_u32 s30, s30, 0x100
	s_addc_u32 s31, s31, 0
	s_cmp_gt_u32 s55, 29
	s_cbranch_scc0 .LBB0_808
	s_and_b64 vcc, exec, s[12:13]
	s_cbranch_vccz .LBB0_811
	s_barrier

; __global__ void __launch_bounds__(NWAVES * 64, 2) mega_fwd(Args args) {
;     extern __shared__ __attribute__((aligned(16))) unsigned char lds[];
	.amdhsa_kernel _Z8mega_fwd4Args
		.amdhsa_group_segment_fixed_size 0
		.amdhsa_private_segment_fixed_size 0
		.amdhsa_kernarg_size 392
		.amdhsa_user_sgpr_count 2
		.amdhsa_user_sgpr_dispatch_ptr 0
		.amdhsa_user_sgpr_queue_ptr 0
		.amdhsa_user_sgpr_kernarg_segment_ptr 1
		.amdhsa_user_sgpr_dispatch_id 0
		.amdhsa_user_sgpr_kernarg_preload_length 0
		.amdhsa_user_sgpr_kernarg_preload_offset 0
		.amdhsa_user_sgpr_private_segment_size 0
		.amdhsa_uses_dynamic_stack 0
		.amdhsa_enable_private_segment 0
		.amdhsa_system_sgpr_workgroup_id_x 1
		.amdhsa_system_sgpr_workgroup_id_y 0
		.amdhsa_system_sgpr_workgroup_id_z 0
		.amdhsa_system_sgpr_workgroup_info 0
		.amdhsa_system_vgpr_workitem_id 0
		.amdhsa_next_free_vgpr 256
		.amdhsa_next_free_sgpr 102
		.amdhsa_accum_offset 256
		.amdhsa_reserve_vcc 1
		.amdhsa_float_round_mode_32 0
		.amdhsa_float_round_mode_16_64 0
		.amdhsa_float_denorm_mode_32 3
		.amdhsa_float_denorm_mode_16_64 3
		.amdhsa_dx10_clamp 1
		.amdhsa_ieee_mode 1
		.amdhsa_fp16_overflow 0
		.amdhsa_tg_split 0
		.amdhsa_exception_fp_ieee_invalid_op 0
		.amdhsa_exception_fp_denorm_src 0
		.amdhsa_exception_fp_ieee_div_zero 0
		.amdhsa_exception_fp_ieee_overflow 0
		.amdhsa_exception_fp_ieee_underflow 0
		.amdhsa_exception_fp_ieee_inexact 0
		.amdhsa_exception_int_div_zero 0
	.end_amdhsa_kernel

; __global__ void __launch_bounds__(NWAVES * 64, 2) mega_fwd(Args args) {
;     extern __shared__ __attribute__((aligned(16))) unsigned char lds[];
amdhsa.kernels:
  - .agpr_count:     0
    .args:
      - .offset:         0
        .size:           136
        .value_kind:     by_value
      - .offset:         136
        .size:           4
        .value_kind:     hidden_block_count_x
      - .offset:         140
        .size:           4
        .value_kind:     hidden_block_count_y
      - .offset:         144
        .size:           4
        .value_kind:     hidden_block_count_z
      - .offset:         148
        .size:           2
        .value_kind:     hidden_group_size_x
      - .offset:         150
        .size:           2
        .value_kind:     hidden_group_size_y
      - .offset:         152
        .size:           2
        .value_kind:     hidden_group_size_z
      - .offset:         154
        .size:           2
        .value_kind:     hidden_remainder_x
      - .offset:         156
        .size:           2
        .value_kind:     hidden_remainder_y
      - .offset:         158
        .size:           2
        .value_kind:     hidden_remainder_z
      - .offset:         176
        .size:           8
        .value_kind:     hidden_global_offset_x
      - .offset:         184
        .size:           8
        .value_kind:     hidden_global_offset_y
      - .offset:         192
        .size:           8
        .value_kind:     hidden_global_offset_z
      - .offset:         200
        .size:           2
        .value_kind:     hidden_grid_dims
      - .offset:         256
        .size:           4
        .value_kind:     hidden_dynamic_lds_size
    .group_segment_fixed_size: 0
    .kernarg_segment_align: 8
    .kernarg_segment_size: 392
    .language:       OpenCL C
    .language_version:
      - 2
      - 0
    .max_flat_workgroup_size: 512
    .name:           _Z8mega_fwd4Args
    .private_segment_fixed_size: 0
    .sgpr_count:     108
    .sgpr_spill_count: 24
    .symbol:         _Z8mega_fwd4Args.kd
    .uniform_work_group_size: 1
    .uses_dynamic_stack: false
    .vgpr_count:     256
    .vgpr_spill_count: 0
    .wavefront_size: 64
